# v27 plus in-proj rope epilogue: cos/sin of the 8 rows prefetched once instead of 16 serialized load-wait round trips
# baseline (speedup 1.0000x reference)
; DI unsigned pk2(float lo, float hi) { f32x2_t v = {lo, hi}; bf16x2_t b = __builtin_convertvector(v, bf16x2_t); return __builtin_bit_cast(unsigned, b); }
; template <class F> DI void epi_iter(const f32x4 (&acc)[2][2][4][2], const Unit& u, int wr, int wc, int fr, int fq, F f) {
;     const int row0 = u.pm * 256 + wr * 64 + fr, col0 = u.pn * 256 + wc * 32 + 8 * fq;
; #pragma unroll
;     for (int ai = 0; ai < 2; ++ai)
; #pragma unroll
;         for (int m = 0; m < 4; ++m)
; #pragma unroll
;             for (int bj = 0; bj < 2; ++bj) { f(row0 + ai * 128 + m * 16, col0 + bj * 128, acc[ai][bj][m][0], acc[ai][bj][m][1]); if ((m == 3) && bj) asm volatile("" ::: "memory"); }
;     DI void operator()(const f32x4 (&acc)[2][2][4][2], const Unit& u, int wr, int wc, int fr, int fq) const {
;         bf16_t* Op = O; const int ld = ldc, lo = rlo, hi = rhi; const float* cp = rc; const float* sp = rsn;
;         epi_iter(acc, u, wr, wc, fr, fq, [&](int row, int col, f32x4 v0, f32x4 v1) {
;             if (col >= lo && col < hi) {
;                 const int i0 = ((col - lo) & 63) >> 1;
;                 const f32x4 c4 = *(const f32x4*)(cp + (size_t)row * 32 + i0), s4 = *(const f32x4*)(sp + (size_t)row * 32 + i0);
;                 const float sc = (col - lo) < 512 ? 0.125f * LOG2E : 1.f;
;                 for (int e = 0; e < 4; ++e) { const float y1 = (v0[e] * c4[e] - v1[e] * s4[e]) * sc, y2 = (v1[e] * c4[e] + v0[e] * s4[e]) * sc; v0[e] = y1; v1[e] = y2; }
;             }
;             u32x4 w; w.x = pk2(v0[0], v0[1]); w.y = pk2(v0[2], v0[3]); w.z = pk2(v1[0], v1[1]); w.w = pk2(v1[2], v1[3]);
;             *(u32x4*)(Op + (size_t)row * ld + col) = w;
.LBB0_237:
	v_lshl_add_u32 v144, s56, 8, v153
	v_lshl_or_b32 v142, s19, 8, v155
	v_ashrrev_i32_e32 v145, 31, v144
	v_cmp_le_i32_e32 vcc, s11, v142
	v_cmp_gt_i32_e64 s[0:1], s12, v142
	v_lshlrev_b64 v[146:147], 5, v[144:145]
	s_and_b64 s[56:57], vcc, s[0:1]
	s_and_saveexec_b64 s[0:1], s[56:57]
	s_cbranch_execz .LBB0_239
	v_lshlrev_b64 v[244:245], 2, v[146:147]
	v_lshlrev_b32_e32 v0, 1, v142
	v_and_b32_e32 v0, 0x70, v0
	v_lshl_add_u64 v[244:245], v[244:245], 0, v[0:1]
	v_lshl_add_u64 v[246:247], s[6:7], 0, v[244:245]
	v_lshl_add_u64 v[244:245], s[66:67], 0, v[244:245]
	global_load_dwordx4 v[170:173], v[244:245], off
	global_load_dwordx4 v[174:177], v[246:247], off
	global_load_dwordx4 v[178:181], v[244:245], off offset:2048
	global_load_dwordx4 v[182:185], v[246:247], off offset:2048
	s_mov_b64 s[2:3], 0x1000
	v_lshl_add_u64 v[244:245], v[244:245], 0, s[2:3]
	v_lshl_add_u64 v[246:247], v[246:247], 0, s[2:3]
	global_load_dwordx4 v[186:189], v[244:245], off
	global_load_dwordx4 v[190:193], v[246:247], off
	global_load_dwordx4 v[212:215], v[244:245], off offset:2048
	global_load_dwordx4 v[216:219], v[246:247], off offset:2048
	s_mov_b64 s[2:3], 0x3000
	v_lshl_add_u64 v[244:245], v[244:245], 0, s[2:3]
	v_lshl_add_u64 v[246:247], v[246:247], 0, s[2:3]
	global_load_dwordx4 v[220:223], v[244:245], off
	global_load_dwordx4 v[224:227], v[246:247], off
	global_load_dwordx4 v[228:231], v[244:245], off offset:2048
	global_load_dwordx4 v[232:235], v[246:247], off offset:2048
	s_mov_b64 s[2:3], 0x1000
	v_lshl_add_u64 v[244:245], v[244:245], 0, s[2:3]
	v_lshl_add_u64 v[246:247], v[246:247], 0, s[2:3]
	global_load_dwordx4 v[236:239], v[244:245], off
	global_load_dwordx4 v[240:243], v[246:247], off
	v_lshlrev_b64 v[162:163], 2, v[146:147]
	v_lshlrev_b32_e32 v0, 1, v142
	v_lshl_add_u64 v[158:159], s[66:67], 0, v[162:163]
	v_and_b32_e32 v0, 0x70, v0
	v_lshl_add_u64 v[162:163], s[6:7], 0, v[162:163]
	v_lshl_add_u64 v[158:159], v[158:159], 0, v[0:1]
	v_lshl_add_u64 v[162:163], v[162:163], 0, v[0:1]
	v_cmp_gt_i32_e32 vcc, s69, v142
	s_waitcnt vmcnt(12)
	v_mov_b32_e32 v158, v170
	v_mov_b32_e32 v159, v171
	v_mov_b32_e32 v160, v172
	v_mov_b32_e32 v161, v173
	v_mov_b32_e32 v162, v174
	v_mov_b32_e32 v163, v175
	v_mov_b32_e32 v164, v176
	v_mov_b32_e32 v165, v177
	v_pk_mul_f32 v[166:167], v[122:123], v[162:163]
	s_nop 0
	v_pk_fma_f32 v[166:167], v[126:127], v[158:159], v[166:167] neg_lo:[0,0,1] neg_hi:[0,0,1]
	v_pk_mul_f32 v[126:127], v[126:127], v[162:163]
	v_mul_f32_e32 v162, v128, v164
	v_pk_fma_f32 v[122:123], v[122:123], v[158:159], v[126:127]
	v_mul_f32_e32 v126, v128, v160
	v_mul_f32_e32 v158, v124, v164
	v_mul_f32_e32 v160, v124, v160
	v_mov_b32_e32 v124, v129
	v_mov_b32_e32 v164, v161
	v_pk_mul_f32 v[168:169], v[124:125], v[164:165]
	v_mov_b32_e32 v128, v125
	v_cndmask_b32_e32 v0, 1.0, v203, vcc
	v_mov_b32_e32 v127, v168
	v_mov_b32_e32 v159, v169
	v_pk_mul_f32 v[124:125], v[128:129], v[164:165]
	v_pk_mul_f32 v[166:167], v[0:1], v[166:167] op_sel_hi:[0,1]
	v_pk_add_f32 v[126:127], v[126:127], v[158:159] neg_lo:[0,1] neg_hi:[0,1]
	v_mov_b32_e32 v161, v124
	v_mov_b32_e32 v163, v125
	v_pk_mul_f32 v[168:169], v[0:1], v[126:127] op_sel_hi:[0,1]
	v_pk_add_f32 v[124:125], v[160:161], v[162:163]
	v_mov_b64_e32 v[126:127], v[166:167]
	v_pk_mul_f32 v[122:123], v[0:1], v[122:123] op_sel_hi:[0,1]
	v_pk_mul_f32 v[124:125], v[0:1], v[124:125] op_sel_hi:[0,1]
	v_mov_b64_e32 v[128:129], v[168:169]
.LBB0_239:
	s_or_b64 exec, exec, s[0:1]
	v_cvt_pk_bf16_f32 v126, v126, v127
	v_cvt_pk_bf16_f32 v127, v128, v129
	v_cvt_pk_bf16_f32 v128, v122, v123
	v_mad_i64_i32 v[122:123], s[0:1], v144, s10, 0
	v_or_b32_e32 v0, 0x80, v142
	v_lshl_add_u64 v[122:123], v[122:123], 1, s[4:5]
	v_ashrrev_i32_e32 v143, 31, v142
	v_cmp_le_i32_e32 vcc, s11, v0
	v_cmp_gt_i32_e64 s[0:1], s12, v0
	v_cvt_pk_bf16_f32 v129, v124, v125
	v_lshl_add_u64 v[122:123], v[142:143], 1, v[122:123]
	s_and_b64 s[0:1], vcc, s[0:1]
	global_store_dwordx4 v[122:123], v[126:129], off
	s_and_saveexec_b64 s[2:3], s[0:1]
	s_cbranch_execz .LBB0_241
	v_lshlrev_b64 v[128:129], 2, v[146:147]
	v_lshlrev_b32_e32 v0, 1, v142
	v_lshl_add_u64 v[124:125], s[66:67], 0, v[128:129]
	v_and_b32_e32 v0, 0x70, v0
	v_lshl_add_u64 v[128:129], s[6:7], 0, v[128:129]
	v_lshl_add_u64 v[124:125], v[124:125], 0, v[0:1]
	v_lshl_add_u64 v[128:129], v[128:129], 0, v[0:1]
	v_cmp_gt_i32_e32 vcc, s82, v142
	v_mov_b32_e32 v124, v170
	v_mov_b32_e32 v125, v171
	v_mov_b32_e32 v126, v172
	v_mov_b32_e32 v127, v173
	v_mov_b32_e32 v158, v174
	v_mov_b32_e32 v159, v175
	v_mov_b32_e32 v160, v176
	v_mov_b32_e32 v161, v177
	v_pk_mul_f32 v[128:129], v[114:115], v[158:159]
	v_cndmask_b32_e32 v0, 1.0, v203, vcc
	v_pk_fma_f32 v[128:129], v[118:119], v[124:125], v[128:129] neg_lo:[0,0,1] neg_hi:[0,0,1]
	v_pk_mul_f32 v[118:119], v[118:119], v[158:159]
	v_pk_mul_f32 v[162:163], v[0:1], v[128:129] op_sel_hi:[0,1]
	v_pk_fma_f32 v[114:115], v[114:115], v[124:125], v[118:119]
	v_mul_f32_e32 v118, v120, v126
	v_mul_f32_e32 v124, v116, v160
	v_mul_f32_e32 v126, v116, v126
	v_mul_f32_e32 v128, v120, v160
	v_mov_b32_e32 v116, v121
	v_mov_b32_e32 v160, v127
	v_pk_mul_f32 v[146:147], v[116:117], v[160:161]
	v_mov_b32_e32 v120, v117
	v_mov_b32_e32 v119, v146
	v_mov_b32_e32 v125, v147
	v_pk_mul_f32 v[116:117], v[120:121], v[160:161]
	v_pk_add_f32 v[118:119], v[118:119], v[124:125] neg_lo:[0,1] neg_hi:[0,1]
	v_mov_b32_e32 v127, v116
	v_mov_b32_e32 v129, v117
	v_pk_mul_f32 v[164:165], v[0:1], v[118:119] op_sel_hi:[0,1]
	v_pk_add_f32 v[116:117], v[126:127], v[128:129]
	v_mov_b64_e32 v[118:119], v[162:163]
	v_pk_mul_f32 v[114:115], v[0:1], v[114:115] op_sel_hi:[0,1]
	v_pk_mul_f32 v[116:117], v[0:1], v[116:117] op_sel_hi:[0,1]
	v_mov_b64_e32 v[120:121], v[164:165]
	global_load_dwordx4 v[170:173], v[244:245], off offset:2048
	global_load_dwordx4 v[174:177], v[246:247], off offset:2048
; DI unsigned pk2(float lo, float hi) { f32x2_t v = {lo, hi}; bf16x2_t b = __builtin_convertvector(v, bf16x2_t); return __builtin_bit_cast(unsigned, b); }
;     DI void operator()(const f32x4 (&acc)[2][2][4][2], const Unit& u, int wr, int wc, int fr, int fq) const {
;     ...
;         epi_iter(acc, u, wr, wc, fr, fq, [&](int row, int col, f32x4 v0, f32x4 v1) {
;             if (col >= lo && col < hi) {
;                 const int i0 = ((col - lo) & 63) >> 1;
;                 const f32x4 c4 = *(const f32x4*)(cp + (size_t)row * 32 + i0), s4 = *(const f32x4*)(sp + (size_t)row * 32 + i0);
;                 const float sc = (col - lo) < 512 ? 0.125f * LOG2E : 1.f;
;                 for (int e = 0; e < 4; ++e) { const float y1 = (v0[e] * c4[e] - v1[e] * s4[e]) * sc, y2 = (v1[e] * c4[e] + v0[e] * s4[e]) * sc; v0[e] = y1; v1[e] = y2; }
;             }
;             u32x4 w; w.x = pk2(v0[0], v0[1]); w.y = pk2(v0[2], v0[3]); w.z = pk2(v1[0], v1[1]); w.w = pk2(v1[2], v1[3]);
;             *(u32x4*)(Op + (size_t)row * ld + col) = w;
.LBB0_241:
	s_or_b64 exec, exec, s[2:3]
	v_cvt_pk_bf16_f32 v118, v118, v119
	v_cvt_pk_bf16_f32 v119, v120, v121
	v_cvt_pk_bf16_f32 v121, v116, v117
	v_or_b32_e32 v116, 16, v144
	v_ashrrev_i32_e32 v117, 31, v116
	v_cvt_pk_bf16_f32 v120, v114, v115
	v_lshlrev_b64 v[114:115], 5, v[116:117]
	global_store_dwordx4 v[122:123], v[118:121], off offset:256
	s_and_saveexec_b64 s[2:3], s[56:57]
	s_cbranch_execz .LBB0_243
	v_lshlrev_b64 v[122:123], 2, v[114:115]
	v_lshlrev_b32_e32 v0, 1, v142
	v_lshl_add_u64 v[118:119], s[66:67], 0, v[122:123]
	v_and_b32_e32 v0, 0x70, v0
	v_lshl_add_u64 v[122:123], s[6:7], 0, v[122:123]
	v_lshl_add_u64 v[118:119], v[118:119], 0, v[0:1]
	v_lshl_add_u64 v[122:123], v[122:123], 0, v[0:1]
	v_cmp_gt_i32_e32 vcc, s69, v142
	s_waitcnt vmcnt(14)
	v_mov_b32_e32 v118, v178
	v_mov_b32_e32 v119, v179
	v_mov_b32_e32 v120, v180
	v_mov_b32_e32 v121, v181
	v_mov_b32_e32 v122, v182
	v_mov_b32_e32 v123, v183
	v_mov_b32_e32 v124, v184
	v_mov_b32_e32 v125, v185
	v_pk_mul_f32 v[126:127], v[106:107], v[122:123]
	s_nop 0
	v_pk_fma_f32 v[126:127], v[110:111], v[118:119], v[126:127] neg_lo:[0,0,1] neg_hi:[0,0,1]
	v_pk_mul_f32 v[110:111], v[110:111], v[122:123]
	v_mul_f32_e32 v122, v112, v124
	v_pk_fma_f32 v[106:107], v[106:107], v[118:119], v[110:111]
	v_mul_f32_e32 v110, v112, v120
	v_mul_f32_e32 v118, v108, v124
	v_mul_f32_e32 v120, v108, v120
	v_mov_b32_e32 v108, v113
	v_mov_b32_e32 v124, v121
	v_pk_mul_f32 v[128:129], v[108:109], v[124:125]
	v_mov_b32_e32 v112, v109
	v_cndmask_b32_e32 v0, 1.0, v203, vcc
	v_mov_b32_e32 v111, v128
	v_mov_b32_e32 v119, v129
	v_pk_mul_f32 v[108:109], v[112:113], v[124:125]
	v_pk_mul_f32 v[126:127], v[0:1], v[126:127] op_sel_hi:[0,1]
	v_pk_add_f32 v[110:111], v[110:111], v[118:119] neg_lo:[0,1] neg_hi:[0,1]
	v_mov_b32_e32 v121, v108
	v_mov_b32_e32 v123, v109
	v_pk_mul_f32 v[128:129], v[0:1], v[110:111] op_sel_hi:[0,1]
	v_pk_add_f32 v[108:109], v[120:121], v[122:123]
	v_mov_b64_e32 v[110:111], v[126:127]
	v_pk_mul_f32 v[106:107], v[0:1], v[106:107] op_sel_hi:[0,1]
	v_pk_mul_f32 v[108:109], v[0:1], v[108:109] op_sel_hi:[0,1]
	v_mov_b64_e32 v[112:113], v[128:129]
.LBB0_243:
	s_or_b64 exec, exec, s[2:3]
	v_cvt_pk_bf16_f32 v110, v110, v111
	v_cvt_pk_bf16_f32 v111, v112, v113
	v_cvt_pk_bf16_f32 v112, v106, v107
	v_mad_i64_i32 v[106:107], s[2:3], v116, s10, 0
	v_lshl_add_u64 v[106:107], v[106:107], 1, s[4:5]
	v_cvt_pk_bf16_f32 v113, v108, v109
	v_lshl_add_u64 v[106:107], v[142:143], 1, v[106:107]
	global_store_dwordx4 v[106:107], v[110:113], off
	s_and_saveexec_b64 s[2:3], s[0:1]
	s_cbranch_execz .LBB0_245
	v_lshlrev_b64 v[112:113], 2, v[114:115]
	v_lshlrev_b32_e32 v0, 1, v142
	v_lshl_add_u64 v[108:109], s[66:67], 0, v[112:113]
	v_and_b32_e32 v0, 0x70, v0
	v_lshl_add_u64 v[112:113], s[6:7], 0, v[112:113]
	v_lshl_add_u64 v[108:109], v[108:109], 0, v[0:1]
	v_lshl_add_u64 v[112:113], v[112:113], 0, v[0:1]
	v_cmp_gt_i32_e32 vcc, s82, v142
	v_mov_b32_e32 v108, v178
	v_mov_b32_e32 v109, v179
	v_mov_b32_e32 v110, v180
	v_mov_b32_e32 v111, v181
	v_mov_b32_e32 v112, v182
	v_mov_b32_e32 v113, v183
	v_mov_b32_e32 v114, v184
	v_mov_b32_e32 v115, v185
	v_pk_mul_f32 v[116:117], v[98:99], v[112:113]
	s_nop 0
	v_pk_fma_f32 v[116:117], v[102:103], v[108:109], v[116:117] neg_lo:[0,0,1] neg_hi:[0,0,1]
	v_pk_mul_f32 v[102:103], v[102:103], v[112:113]
	v_mul_f32_e32 v112, v104, v114
	v_pk_fma_f32 v[98:99], v[98:99], v[108:109], v[102:103]
	v_mul_f32_e32 v102, v104, v110
	v_mul_f32_e32 v108, v100, v114
	v_mul_f32_e32 v110, v100, v110
	v_mov_b32_e32 v100, v105
	v_mov_b32_e32 v114, v111
	v_pk_mul_f32 v[118:119], v[100:101], v[114:115]
	v_mov_b32_e32 v104, v101
	v_cndmask_b32_e32 v0, 1.0, v203, vcc
	v_mov_b32_e32 v103, v118
	v_mov_b32_e32 v109, v119
	v_pk_mul_f32 v[100:101], v[104:105], v[114:115]
	v_pk_mul_f32 v[116:117], v[0:1], v[116:117] op_sel_hi:[0,1]
	v_pk_add_f32 v[102:103], v[102:103], v[108:109] neg_lo:[0,1] neg_hi:[0,1]
	v_mov_b32_e32 v111, v100
	v_mov_b32_e32 v113, v101
	v_pk_mul_f32 v[118:119], v[0:1], v[102:103] op_sel_hi:[0,1]
	v_pk_add_f32 v[100:101], v[110:111], v[112:113]
	v_mov_b64_e32 v[102:103], v[116:117]
	v_pk_mul_f32 v[98:99], v[0:1], v[98:99] op_sel_hi:[0,1]
	v_pk_mul_f32 v[100:101], v[0:1], v[100:101] op_sel_hi:[0,1]
	v_mov_b64_e32 v[104:105], v[118:119]
.LBB0_245:
	s_or_b64 exec, exec, s[2:3]
	v_cvt_pk_bf16_f32 v102, v102, v103
	v_cvt_pk_bf16_f32 v103, v104, v105
	v_cvt_pk_bf16_f32 v105, v100, v101
	v_or_b32_e32 v100, 32, v144
	v_ashrrev_i32_e32 v101, 31, v100
	v_cvt_pk_bf16_f32 v104, v98, v99
	v_lshlrev_b64 v[98:99], 5, v[100:101]
	global_store_dwordx4 v[106:107], v[102:105], off offset:256
	s_and_saveexec_b64 s[2:3], s[56:57]
	s_cbranch_execz .LBB0_247
	v_lshlrev_b64 v[106:107], 2, v[98:99]
	v_lshlrev_b32_e32 v0, 1, v142
	v_lshl_add_u64 v[102:103], s[66:67], 0, v[106:107]
	v_and_b32_e32 v0, 0x70, v0
	v_lshl_add_u64 v[106:107], s[6:7], 0, v[106:107]
	v_lshl_add_u64 v[102:103], v[102:103], 0, v[0:1]
	v_lshl_add_u64 v[106:107], v[106:107], 0, v[0:1]
	v_cmp_gt_i32_e32 vcc, s69, v142
	s_waitcnt vmcnt(14)
	v_mov_b32_e32 v102, v186
	v_mov_b32_e32 v103, v187
	v_mov_b32_e32 v104, v188
	v_mov_b32_e32 v105, v189
	v_mov_b32_e32 v106, v190
	v_mov_b32_e32 v107, v191
	v_mov_b32_e32 v108, v192
	v_mov_b32_e32 v109, v193
	v_pk_mul_f32 v[110:111], v[90:91], v[106:107]
	s_nop 0
	v_pk_fma_f32 v[110:111], v[94:95], v[102:103], v[110:111] neg_lo:[0,0,1] neg_hi:[0,0,1]
	v_pk_mul_f32 v[94:95], v[94:95], v[106:107]
	v_mul_f32_e32 v106, v96, v108
	v_pk_fma_f32 v[90:91], v[90:91], v[102:103], v[94:95]
	v_mul_f32_e32 v94, v96, v104
	v_mul_f32_e32 v102, v92, v108
	v_mul_f32_e32 v104, v92, v104
	v_mov_b32_e32 v92, v97
	v_mov_b32_e32 v108, v105
	v_pk_mul_f32 v[112:113], v[92:93], v[108:109]
	v_mov_b32_e32 v96, v93
	v_cndmask_b32_e32 v0, 1.0, v203, vcc
	v_mov_b32_e32 v95, v112
	v_mov_b32_e32 v103, v113
	v_pk_mul_f32 v[92:93], v[96:97], v[108:109]
	v_pk_mul_f32 v[110:111], v[0:1], v[110:111] op_sel_hi:[0,1]
	v_pk_add_f32 v[94:95], v[94:95], v[102:103] neg_lo:[0,1] neg_hi:[0,1]
	v_mov_b32_e32 v105, v92
	v_mov_b32_e32 v107, v93
	v_pk_mul_f32 v[112:113], v[0:1], v[94:95] op_sel_hi:[0,1]
	v_pk_add_f32 v[92:93], v[104:105], v[106:107]
	v_mov_b64_e32 v[94:95], v[110:111]
	v_pk_mul_f32 v[90:91], v[0:1], v[90:91] op_sel_hi:[0,1]
	v_pk_mul_f32 v[92:93], v[0:1], v[92:93] op_sel_hi:[0,1]
	v_mov_b64_e32 v[96:97], v[112:113]
; DI unsigned pk2(float lo, float hi) { f32x2_t v = {lo, hi}; bf16x2_t b = __builtin_convertvector(v, bf16x2_t); return __builtin_bit_cast(unsigned, b); }
;     DI void operator()(const f32x4 (&acc)[2][2][4][2], const Unit& u, int wr, int wc, int fr, int fq) const {
;     ...
;         epi_iter(acc, u, wr, wc, fr, fq, [&](int row, int col, f32x4 v0, f32x4 v1) {
;             if (col >= lo && col < hi) {
;                 const int i0 = ((col - lo) & 63) >> 1;
;                 const f32x4 c4 = *(const f32x4*)(cp + (size_t)row * 32 + i0), s4 = *(const f32x4*)(sp + (size_t)row * 32 + i0);
;                 const float sc = (col - lo) < 512 ? 0.125f * LOG2E : 1.f;
;                 for (int e = 0; e < 4; ++e) { const float y1 = (v0[e] * c4[e] - v1[e] * s4[e]) * sc, y2 = (v1[e] * c4[e] + v0[e] * s4[e]) * sc; v0[e] = y1; v1[e] = y2; }
;             }
;             u32x4 w; w.x = pk2(v0[0], v0[1]); w.y = pk2(v0[2], v0[3]); w.z = pk2(v1[0], v1[1]); w.w = pk2(v1[2], v1[3]);
;             *(u32x4*)(Op + (size_t)row * ld + col) = w;
.LBB0_247:
	s_or_b64 exec, exec, s[2:3]
	v_cvt_pk_bf16_f32 v94, v94, v95
	v_cvt_pk_bf16_f32 v95, v96, v97
	v_cvt_pk_bf16_f32 v96, v90, v91
	v_mad_i64_i32 v[90:91], s[2:3], v100, s10, 0
	v_lshl_add_u64 v[90:91], v[90:91], 1, s[4:5]
	v_cvt_pk_bf16_f32 v97, v92, v93
	v_lshl_add_u64 v[90:91], v[142:143], 1, v[90:91]
	global_store_dwordx4 v[90:91], v[94:97], off
	s_and_saveexec_b64 s[2:3], s[0:1]
	s_cbranch_execz .LBB0_249
	v_lshlrev_b64 v[96:97], 2, v[98:99]
	v_lshlrev_b32_e32 v0, 1, v142
	v_lshl_add_u64 v[92:93], s[66:67], 0, v[96:97]
	v_and_b32_e32 v0, 0x70, v0
	v_lshl_add_u64 v[96:97], s[6:7], 0, v[96:97]
	v_lshl_add_u64 v[92:93], v[92:93], 0, v[0:1]
	v_lshl_add_u64 v[96:97], v[96:97], 0, v[0:1]
	v_cmp_gt_i32_e32 vcc, s82, v142
	v_mov_b32_e32 v92, v186
	v_mov_b32_e32 v93, v187
	v_mov_b32_e32 v94, v188
	v_mov_b32_e32 v95, v189
	v_mov_b32_e32 v96, v190
	v_mov_b32_e32 v97, v191
	v_mov_b32_e32 v98, v192
	v_mov_b32_e32 v99, v193
	v_pk_mul_f32 v[100:101], v[82:83], v[96:97]
	s_nop 0
	v_pk_fma_f32 v[100:101], v[86:87], v[92:93], v[100:101] neg_lo:[0,0,1] neg_hi:[0,0,1]
	v_pk_mul_f32 v[86:87], v[86:87], v[96:97]
	v_mul_f32_e32 v96, v88, v98
	v_pk_fma_f32 v[82:83], v[82:83], v[92:93], v[86:87]
	v_mul_f32_e32 v86, v88, v94
	v_mul_f32_e32 v92, v84, v98
	v_mul_f32_e32 v94, v84, v94
	v_mov_b32_e32 v84, v89
	v_mov_b32_e32 v98, v95
	v_pk_mul_f32 v[102:103], v[84:85], v[98:99]
	v_mov_b32_e32 v88, v85
	v_cndmask_b32_e32 v0, 1.0, v203, vcc
	v_mov_b32_e32 v87, v102
	v_mov_b32_e32 v93, v103
	v_pk_mul_f32 v[84:85], v[88:89], v[98:99]
	v_pk_mul_f32 v[100:101], v[0:1], v[100:101] op_sel_hi:[0,1]
	v_pk_add_f32 v[86:87], v[86:87], v[92:93] neg_lo:[0,1] neg_hi:[0,1]
	v_mov_b32_e32 v95, v84
	v_mov_b32_e32 v97, v85
	v_pk_mul_f32 v[102:103], v[0:1], v[86:87] op_sel_hi:[0,1]
	v_pk_add_f32 v[84:85], v[94:95], v[96:97]
	v_mov_b64_e32 v[86:87], v[100:101]
	v_pk_mul_f32 v[82:83], v[0:1], v[82:83] op_sel_hi:[0,1]
	v_pk_mul_f32 v[84:85], v[0:1], v[84:85] op_sel_hi:[0,1]
	v_mov_b64_e32 v[88:89], v[102:103]
.LBB0_249:
	s_or_b64 exec, exec, s[2:3]
	v_cvt_pk_bf16_f32 v86, v86, v87
	v_cvt_pk_bf16_f32 v87, v88, v89
	v_cvt_pk_bf16_f32 v89, v84, v85
	v_or_b32_e32 v84, 48, v144
	v_ashrrev_i32_e32 v85, 31, v84
	v_cvt_pk_bf16_f32 v88, v82, v83
	v_lshlrev_b64 v[82:83], 5, v[84:85]
	global_store_dwordx4 v[90:91], v[86:89], off offset:256
	s_and_saveexec_b64 s[2:3], s[56:57]
	s_cbranch_execz .LBB0_251
	v_lshlrev_b64 v[90:91], 2, v[82:83]
	v_lshlrev_b32_e32 v0, 1, v142
	v_lshl_add_u64 v[86:87], s[66:67], 0, v[90:91]
	v_and_b32_e32 v0, 0x70, v0
	v_lshl_add_u64 v[90:91], s[6:7], 0, v[90:91]
	v_lshl_add_u64 v[86:87], v[86:87], 0, v[0:1]
	v_lshl_add_u64 v[90:91], v[90:91], 0, v[0:1]
	v_cmp_gt_i32_e32 vcc, s69, v142
	s_waitcnt vmcnt(14)
	v_mov_b32_e32 v86, v212
	v_mov_b32_e32 v87, v213
	v_mov_b32_e32 v88, v214
	v_mov_b32_e32 v89, v215
	v_mov_b32_e32 v90, v216
	v_mov_b32_e32 v91, v217
	v_mov_b32_e32 v92, v218
	v_mov_b32_e32 v93, v219
	v_pk_mul_f32 v[94:95], v[74:75], v[90:91]
	s_nop 0
	v_pk_fma_f32 v[94:95], v[78:79], v[86:87], v[94:95] neg_lo:[0,0,1] neg_hi:[0,0,1]
	v_pk_mul_f32 v[78:79], v[78:79], v[90:91]
	v_mul_f32_e32 v90, v80, v92
	v_pk_fma_f32 v[74:75], v[74:75], v[86:87], v[78:79]
	v_mul_f32_e32 v78, v80, v88
	v_mul_f32_e32 v86, v76, v92
	v_mul_f32_e32 v88, v76, v88
	v_mov_b32_e32 v76, v81
	v_mov_b32_e32 v92, v89
	v_pk_mul_f32 v[96:97], v[76:77], v[92:93]
	v_mov_b32_e32 v80, v77
	v_cndmask_b32_e32 v0, 1.0, v203, vcc
	v_mov_b32_e32 v79, v96
	v_mov_b32_e32 v87, v97
	v_pk_mul_f32 v[76:77], v[80:81], v[92:93]
	v_pk_mul_f32 v[94:95], v[0:1], v[94:95] op_sel_hi:[0,1]
	v_pk_add_f32 v[78:79], v[78:79], v[86:87] neg_lo:[0,1] neg_hi:[0,1]
	v_mov_b32_e32 v89, v76
	v_mov_b32_e32 v91, v77
	v_pk_mul_f32 v[96:97], v[0:1], v[78:79] op_sel_hi:[0,1]
	v_pk_add_f32 v[76:77], v[88:89], v[90:91]
	v_mov_b64_e32 v[78:79], v[94:95]
	v_pk_mul_f32 v[74:75], v[0:1], v[74:75] op_sel_hi:[0,1]
	v_pk_mul_f32 v[76:77], v[0:1], v[76:77] op_sel_hi:[0,1]
	v_mov_b64_e32 v[80:81], v[96:97]
.LBB0_251:
	s_or_b64 exec, exec, s[2:3]
	v_cvt_pk_bf16_f32 v78, v78, v79
	v_cvt_pk_bf16_f32 v79, v80, v81
	v_cvt_pk_bf16_f32 v80, v74, v75
	v_mad_i64_i32 v[74:75], s[2:3], v84, s10, 0
	v_lshl_add_u64 v[74:75], v[74:75], 1, s[4:5]
	v_cvt_pk_bf16_f32 v81, v76, v77
	v_lshl_add_u64 v[74:75], v[142:143], 1, v[74:75]
	global_store_dwordx4 v[74:75], v[78:81], off
	s_and_saveexec_b64 s[2:3], s[0:1]
	s_cbranch_execz .LBB0_253
	v_lshlrev_b64 v[80:81], 2, v[82:83]
	v_lshlrev_b32_e32 v0, 1, v142
	v_lshl_add_u64 v[76:77], s[66:67], 0, v[80:81]
	v_and_b32_e32 v0, 0x70, v0
	v_lshl_add_u64 v[80:81], s[6:7], 0, v[80:81]
	v_lshl_add_u64 v[76:77], v[76:77], 0, v[0:1]
	v_lshl_add_u64 v[80:81], v[80:81], 0, v[0:1]
	v_cmp_gt_i32_e32 vcc, s82, v142
	v_mov_b32_e32 v76, v212
	v_mov_b32_e32 v77, v213
	v_mov_b32_e32 v78, v214
	v_mov_b32_e32 v79, v215
	v_mov_b32_e32 v80, v216
	v_mov_b32_e32 v81, v217
	v_mov_b32_e32 v82, v218
	v_mov_b32_e32 v83, v219
	v_pk_mul_f32 v[84:85], v[66:67], v[80:81]
	s_nop 0
	v_pk_fma_f32 v[84:85], v[70:71], v[76:77], v[84:85] neg_lo:[0,0,1] neg_hi:[0,0,1]
	v_pk_mul_f32 v[70:71], v[70:71], v[80:81]
	v_mul_f32_e32 v80, v72, v82
	v_pk_fma_f32 v[66:67], v[66:67], v[76:77], v[70:71]
	v_mul_f32_e32 v70, v72, v78
	v_mul_f32_e32 v76, v68, v82
	v_mul_f32_e32 v78, v68, v78
	v_mov_b32_e32 v68, v73
	v_mov_b32_e32 v82, v79
	v_pk_mul_f32 v[86:87], v[68:69], v[82:83]
	v_mov_b32_e32 v72, v69
	v_cndmask_b32_e32 v0, 1.0, v203, vcc
	v_mov_b32_e32 v71, v86
	v_mov_b32_e32 v77, v87
	v_pk_mul_f32 v[68:69], v[72:73], v[82:83]
	v_pk_mul_f32 v[84:85], v[0:1], v[84:85] op_sel_hi:[0,1]
	v_pk_add_f32 v[70:71], v[70:71], v[76:77] neg_lo:[0,1] neg_hi:[0,1]
	v_mov_b32_e32 v79, v68
	v_mov_b32_e32 v81, v69
	v_pk_mul_f32 v[86:87], v[0:1], v[70:71] op_sel_hi:[0,1]
	v_pk_add_f32 v[68:69], v[78:79], v[80:81]
	v_mov_b64_e32 v[70:71], v[84:85]
	v_pk_mul_f32 v[66:67], v[0:1], v[66:67] op_sel_hi:[0,1]
	v_pk_mul_f32 v[68:69], v[0:1], v[68:69] op_sel_hi:[0,1]
	v_mov_b64_e32 v[72:73], v[86:87]
; DI unsigned pk2(float lo, float hi) { f32x2_t v = {lo, hi}; bf16x2_t b = __builtin_convertvector(v, bf16x2_t); return __builtin_bit_cast(unsigned, b); }
;     DI void operator()(const f32x4 (&acc)[2][2][4][2], const Unit& u, int wr, int wc, int fr, int fq) const {
;     ...
;         epi_iter(acc, u, wr, wc, fr, fq, [&](int row, int col, f32x4 v0, f32x4 v1) {
;             if (col >= lo && col < hi) {
;                 const int i0 = ((col - lo) & 63) >> 1;
;                 const f32x4 c4 = *(const f32x4*)(cp + (size_t)row * 32 + i0), s4 = *(const f32x4*)(sp + (size_t)row * 32 + i0);
;                 const float sc = (col - lo) < 512 ? 0.125f * LOG2E : 1.f;
;                 for (int e = 0; e < 4; ++e) { const float y1 = (v0[e] * c4[e] - v1[e] * s4[e]) * sc, y2 = (v1[e] * c4[e] + v0[e] * s4[e]) * sc; v0[e] = y1; v1[e] = y2; }
;             }
;             u32x4 w; w.x = pk2(v0[0], v0[1]); w.y = pk2(v0[2], v0[3]); w.z = pk2(v1[0], v1[1]); w.w = pk2(v1[2], v1[3]);
;             *(u32x4*)(Op + (size_t)row * ld + col) = w;
.LBB0_253:
	s_or_b64 exec, exec, s[2:3]
	v_cvt_pk_bf16_f32 v70, v70, v71
	v_cvt_pk_bf16_f32 v71, v72, v73
	v_cvt_pk_bf16_f32 v72, v66, v67
	v_cvt_pk_bf16_f32 v73, v68, v69
	global_store_dwordx4 v[74:75], v[70:73], off offset:256
	v_add_u32_e32 v68, 0x80, v144
	v_ashrrev_i32_e32 v69, 31, v68
	v_lshlrev_b64 v[66:67], 5, v[68:69]
	s_and_saveexec_b64 s[2:3], s[56:57]
	s_cbranch_execz .LBB0_255
	v_lshlrev_b64 v[74:75], 2, v[66:67]
	v_lshlrev_b32_e32 v0, 1, v142
	v_lshl_add_u64 v[70:71], s[66:67], 0, v[74:75]
	v_and_b32_e32 v0, 0x70, v0
	v_lshl_add_u64 v[74:75], s[6:7], 0, v[74:75]
	v_lshl_add_u64 v[70:71], v[70:71], 0, v[0:1]
	v_lshl_add_u64 v[74:75], v[74:75], 0, v[0:1]
	v_cmp_gt_i32_e32 vcc, s69, v142
	s_waitcnt vmcnt(14)
	v_mov_b32_e32 v70, v220
	v_mov_b32_e32 v71, v221
	v_mov_b32_e32 v72, v222
	v_mov_b32_e32 v73, v223
	v_mov_b32_e32 v74, v224
	v_mov_b32_e32 v75, v225
	v_mov_b32_e32 v76, v226
	v_mov_b32_e32 v77, v227
	v_pk_mul_f32 v[78:79], v[58:59], v[74:75]
	s_nop 0
	v_pk_fma_f32 v[78:79], v[62:63], v[70:71], v[78:79] neg_lo:[0,0,1] neg_hi:[0,0,1]
	v_pk_mul_f32 v[62:63], v[62:63], v[74:75]
	v_mul_f32_e32 v74, v64, v76
	v_pk_fma_f32 v[58:59], v[58:59], v[70:71], v[62:63]
	v_mul_f32_e32 v62, v64, v72
	v_mul_f32_e32 v70, v60, v76
	v_mul_f32_e32 v72, v60, v72
	v_mov_b32_e32 v60, v65
	v_mov_b32_e32 v76, v73
	v_pk_mul_f32 v[80:81], v[60:61], v[76:77]
	v_mov_b32_e32 v64, v61
	v_cndmask_b32_e32 v0, 1.0, v203, vcc
	v_mov_b32_e32 v63, v80
	v_mov_b32_e32 v71, v81
	v_pk_mul_f32 v[60:61], v[64:65], v[76:77]
	v_pk_mul_f32 v[78:79], v[0:1], v[78:79] op_sel_hi:[0,1]
	v_pk_add_f32 v[62:63], v[62:63], v[70:71] neg_lo:[0,1] neg_hi:[0,1]
	v_mov_b32_e32 v73, v60
	v_mov_b32_e32 v75, v61
	v_pk_mul_f32 v[80:81], v[0:1], v[62:63] op_sel_hi:[0,1]
	v_pk_add_f32 v[60:61], v[72:73], v[74:75]
	v_mov_b64_e32 v[62:63], v[78:79]
	v_pk_mul_f32 v[58:59], v[0:1], v[58:59] op_sel_hi:[0,1]
	v_pk_mul_f32 v[60:61], v[0:1], v[60:61] op_sel_hi:[0,1]
	v_mov_b64_e32 v[64:65], v[80:81]
.LBB0_255:
	s_or_b64 exec, exec, s[2:3]
	v_cvt_pk_bf16_f32 v62, v62, v63
	v_cvt_pk_bf16_f32 v63, v64, v65
	v_cvt_pk_bf16_f32 v64, v58, v59
	v_mad_i64_i32 v[58:59], s[2:3], v68, s10, 0
	v_lshl_add_u64 v[58:59], v[58:59], 1, s[4:5]
	v_cvt_pk_bf16_f32 v65, v60, v61
	v_lshl_add_u64 v[58:59], v[142:143], 1, v[58:59]
	global_store_dwordx4 v[58:59], v[62:65], off
	s_and_saveexec_b64 s[2:3], s[0:1]
	s_cbranch_execz .LBB0_257
	v_lshlrev_b64 v[64:65], 2, v[66:67]
	v_lshlrev_b32_e32 v0, 1, v142
	v_lshl_add_u64 v[60:61], s[66:67], 0, v[64:65]
	v_and_b32_e32 v0, 0x70, v0
	v_lshl_add_u64 v[64:65], s[6:7], 0, v[64:65]
	v_lshl_add_u64 v[60:61], v[60:61], 0, v[0:1]
	v_lshl_add_u64 v[64:65], v[64:65], 0, v[0:1]
	v_cmp_gt_i32_e32 vcc, s82, v142
	v_mov_b32_e32 v60, v220
	v_mov_b32_e32 v61, v221
	v_mov_b32_e32 v62, v222
	v_mov_b32_e32 v63, v223
	v_mov_b32_e32 v64, v224
	v_mov_b32_e32 v65, v225
	v_mov_b32_e32 v66, v226
	v_mov_b32_e32 v67, v227
	v_pk_mul_f32 v[68:69], v[50:51], v[64:65]
	s_nop 0
	v_pk_fma_f32 v[68:69], v[54:55], v[60:61], v[68:69] neg_lo:[0,0,1] neg_hi:[0,0,1]
	v_pk_mul_f32 v[54:55], v[54:55], v[64:65]
	v_mul_f32_e32 v64, v56, v66
	v_pk_fma_f32 v[50:51], v[50:51], v[60:61], v[54:55]
	v_mul_f32_e32 v54, v56, v62
	v_mul_f32_e32 v60, v52, v66
	v_mul_f32_e32 v62, v52, v62
	v_mov_b32_e32 v52, v57
	v_mov_b32_e32 v66, v63
	v_pk_mul_f32 v[70:71], v[52:53], v[66:67]
	v_mov_b32_e32 v56, v53
	v_cndmask_b32_e32 v0, 1.0, v203, vcc
	v_mov_b32_e32 v55, v70
	v_mov_b32_e32 v61, v71
	v_pk_mul_f32 v[52:53], v[56:57], v[66:67]
	v_pk_mul_f32 v[68:69], v[0:1], v[68:69] op_sel_hi:[0,1]
	v_pk_add_f32 v[54:55], v[54:55], v[60:61] neg_lo:[0,1] neg_hi:[0,1]
	v_mov_b32_e32 v63, v52
	v_mov_b32_e32 v65, v53
	v_pk_mul_f32 v[70:71], v[0:1], v[54:55] op_sel_hi:[0,1]
	v_pk_add_f32 v[52:53], v[62:63], v[64:65]
	v_mov_b64_e32 v[54:55], v[68:69]
	v_pk_mul_f32 v[50:51], v[0:1], v[50:51] op_sel_hi:[0,1]
	v_pk_mul_f32 v[52:53], v[0:1], v[52:53] op_sel_hi:[0,1]
	v_mov_b64_e32 v[56:57], v[70:71]
.LBB0_257:
	s_or_b64 exec, exec, s[2:3]
	v_cvt_pk_bf16_f32 v54, v54, v55
	v_cvt_pk_bf16_f32 v55, v56, v57
	v_cvt_pk_bf16_f32 v57, v52, v53
	v_add_u32_e32 v52, 0x90, v144
	v_ashrrev_i32_e32 v53, 31, v52
	v_cvt_pk_bf16_f32 v56, v50, v51
	v_lshlrev_b64 v[50:51], 5, v[52:53]
	global_store_dwordx4 v[58:59], v[54:57], off offset:256
	s_and_saveexec_b64 s[2:3], s[56:57]
	s_cbranch_execz .LBB0_259
	v_lshlrev_b64 v[58:59], 2, v[50:51]
	v_lshlrev_b32_e32 v0, 1, v142
	v_lshl_add_u64 v[54:55], s[66:67], 0, v[58:59]
	v_and_b32_e32 v0, 0x70, v0
	v_lshl_add_u64 v[58:59], s[6:7], 0, v[58:59]
	v_lshl_add_u64 v[54:55], v[54:55], 0, v[0:1]
	v_lshl_add_u64 v[58:59], v[58:59], 0, v[0:1]
	v_cmp_gt_i32_e32 vcc, s69, v142
	s_waitcnt vmcnt(14)
	v_mov_b32_e32 v54, v228
	v_mov_b32_e32 v55, v229
	v_mov_b32_e32 v56, v230
	v_mov_b32_e32 v57, v231
	v_mov_b32_e32 v58, v232
	v_mov_b32_e32 v59, v233
	v_mov_b32_e32 v60, v234
	v_mov_b32_e32 v61, v235
	v_pk_mul_f32 v[62:63], v[42:43], v[58:59]
	s_nop 0
	v_pk_fma_f32 v[62:63], v[46:47], v[54:55], v[62:63] neg_lo:[0,0,1] neg_hi:[0,0,1]
	v_pk_mul_f32 v[46:47], v[46:47], v[58:59]
	v_mul_f32_e32 v58, v48, v60
	v_pk_fma_f32 v[42:43], v[42:43], v[54:55], v[46:47]
	v_mul_f32_e32 v46, v48, v56
	v_mul_f32_e32 v54, v44, v60
	v_mul_f32_e32 v56, v44, v56
	v_mov_b32_e32 v44, v49
	v_mov_b32_e32 v60, v57
	v_pk_mul_f32 v[64:65], v[44:45], v[60:61]
	v_mov_b32_e32 v48, v45
	v_cndmask_b32_e32 v0, 1.0, v203, vcc
	v_mov_b32_e32 v47, v64
	v_mov_b32_e32 v55, v65
	v_pk_mul_f32 v[44:45], v[48:49], v[60:61]
	v_pk_mul_f32 v[62:63], v[0:1], v[62:63] op_sel_hi:[0,1]
	v_pk_add_f32 v[46:47], v[46:47], v[54:55] neg_lo:[0,1] neg_hi:[0,1]
	v_mov_b32_e32 v57, v44
	v_mov_b32_e32 v59, v45
	v_pk_mul_f32 v[64:65], v[0:1], v[46:47] op_sel_hi:[0,1]
	v_pk_add_f32 v[44:45], v[56:57], v[58:59]
	v_mov_b64_e32 v[46:47], v[62:63]
	v_pk_mul_f32 v[42:43], v[0:1], v[42:43] op_sel_hi:[0,1]
	v_pk_mul_f32 v[44:45], v[0:1], v[44:45] op_sel_hi:[0,1]
	v_mov_b64_e32 v[48:49], v[64:65]
; DI unsigned pk2(float lo, float hi) { f32x2_t v = {lo, hi}; bf16x2_t b = __builtin_convertvector(v, bf16x2_t); return __builtin_bit_cast(unsigned, b); }
;     DI void operator()(const f32x4 (&acc)[2][2][4][2], const Unit& u, int wr, int wc, int fr, int fq) const {
;     ...
;         epi_iter(acc, u, wr, wc, fr, fq, [&](int row, int col, f32x4 v0, f32x4 v1) {
;             if (col >= lo && col < hi) {
;                 const int i0 = ((col - lo) & 63) >> 1;
;                 const f32x4 c4 = *(const f32x4*)(cp + (size_t)row * 32 + i0), s4 = *(const f32x4*)(sp + (size_t)row * 32 + i0);
;                 const float sc = (col - lo) < 512 ? 0.125f * LOG2E : 1.f;
;                 for (int e = 0; e < 4; ++e) { const float y1 = (v0[e] * c4[e] - v1[e] * s4[e]) * sc, y2 = (v1[e] * c4[e] + v0[e] * s4[e]) * sc; v0[e] = y1; v1[e] = y2; }
;             }
;             u32x4 w; w.x = pk2(v0[0], v0[1]); w.y = pk2(v0[2], v0[3]); w.z = pk2(v1[0], v1[1]); w.w = pk2(v1[2], v1[3]);
;             *(u32x4*)(Op + (size_t)row * ld + col) = w;
.LBB0_259:
	s_or_b64 exec, exec, s[2:3]
	v_cvt_pk_bf16_f32 v46, v46, v47
	v_cvt_pk_bf16_f32 v47, v48, v49
	v_cvt_pk_bf16_f32 v48, v42, v43
	v_mad_i64_i32 v[42:43], s[2:3], v52, s10, 0
	v_lshl_add_u64 v[42:43], v[42:43], 1, s[4:5]
	v_cvt_pk_bf16_f32 v49, v44, v45
	v_lshl_add_u64 v[42:43], v[142:143], 1, v[42:43]
	global_store_dwordx4 v[42:43], v[46:49], off
	s_and_saveexec_b64 s[2:3], s[0:1]
	s_cbranch_execz .LBB0_261
	v_lshlrev_b64 v[48:49], 2, v[50:51]
	v_lshlrev_b32_e32 v0, 1, v142
	v_lshl_add_u64 v[44:45], s[66:67], 0, v[48:49]
	v_and_b32_e32 v0, 0x70, v0
	v_lshl_add_u64 v[48:49], s[6:7], 0, v[48:49]
	v_lshl_add_u64 v[44:45], v[44:45], 0, v[0:1]
	v_lshl_add_u64 v[48:49], v[48:49], 0, v[0:1]
	v_cmp_gt_i32_e32 vcc, s82, v142
	v_mov_b32_e32 v44, v228
	v_mov_b32_e32 v45, v229
	v_mov_b32_e32 v46, v230
	v_mov_b32_e32 v47, v231
	v_mov_b32_e32 v48, v232
	v_mov_b32_e32 v49, v233
	v_mov_b32_e32 v50, v234
	v_mov_b32_e32 v51, v235
	v_pk_mul_f32 v[52:53], v[34:35], v[48:49]
	s_nop 0
	v_pk_fma_f32 v[52:53], v[38:39], v[44:45], v[52:53] neg_lo:[0,0,1] neg_hi:[0,0,1]
	v_pk_mul_f32 v[38:39], v[38:39], v[48:49]
	v_mul_f32_e32 v48, v40, v50
	v_pk_fma_f32 v[34:35], v[34:35], v[44:45], v[38:39]
	v_mul_f32_e32 v38, v40, v46
	v_mul_f32_e32 v44, v36, v50
	v_mul_f32_e32 v46, v36, v46
	v_mov_b32_e32 v36, v41
	v_mov_b32_e32 v50, v47
	v_pk_mul_f32 v[54:55], v[36:37], v[50:51]
	v_mov_b32_e32 v40, v37
	v_cndmask_b32_e32 v0, 1.0, v203, vcc
	v_mov_b32_e32 v39, v54
	v_mov_b32_e32 v45, v55
	v_pk_mul_f32 v[36:37], v[40:41], v[50:51]
	v_pk_mul_f32 v[52:53], v[0:1], v[52:53] op_sel_hi:[0,1]
	v_pk_add_f32 v[38:39], v[38:39], v[44:45] neg_lo:[0,1] neg_hi:[0,1]
	v_mov_b32_e32 v47, v36
	v_mov_b32_e32 v49, v37
	v_pk_mul_f32 v[54:55], v[0:1], v[38:39] op_sel_hi:[0,1]
	v_pk_add_f32 v[36:37], v[46:47], v[48:49]
	v_mov_b64_e32 v[38:39], v[52:53]
	v_pk_mul_f32 v[34:35], v[0:1], v[34:35] op_sel_hi:[0,1]
	v_pk_mul_f32 v[36:37], v[0:1], v[36:37] op_sel_hi:[0,1]
	v_mov_b64_e32 v[40:41], v[54:55]
.LBB0_261:
	s_or_b64 exec, exec, s[2:3]
	v_cvt_pk_bf16_f32 v38, v38, v39
	v_cvt_pk_bf16_f32 v39, v40, v41
	v_cvt_pk_bf16_f32 v41, v36, v37
	v_add_u32_e32 v36, 0xa0, v144
	v_ashrrev_i32_e32 v37, 31, v36
	v_cvt_pk_bf16_f32 v40, v34, v35
	v_lshlrev_b64 v[34:35], 5, v[36:37]
	global_store_dwordx4 v[42:43], v[38:41], off offset:256
	s_and_saveexec_b64 s[2:3], s[56:57]
	s_cbranch_execz .LBB0_263
	v_lshlrev_b64 v[42:43], 2, v[34:35]
	v_lshlrev_b32_e32 v0, 1, v142
	v_lshl_add_u64 v[38:39], s[66:67], 0, v[42:43]
	v_and_b32_e32 v0, 0x70, v0
	v_lshl_add_u64 v[42:43], s[6:7], 0, v[42:43]
	v_lshl_add_u64 v[38:39], v[38:39], 0, v[0:1]
	v_lshl_add_u64 v[42:43], v[42:43], 0, v[0:1]
	v_cmp_gt_i32_e32 vcc, s69, v142
	s_waitcnt vmcnt(14)
	v_mov_b32_e32 v38, v236
	v_mov_b32_e32 v39, v237
	v_mov_b32_e32 v40, v238
	v_mov_b32_e32 v41, v239
	v_mov_b32_e32 v42, v240
	v_mov_b32_e32 v43, v241
	v_mov_b32_e32 v44, v242
	v_mov_b32_e32 v45, v243
	v_pk_mul_f32 v[46:47], v[26:27], v[42:43]
	s_nop 0
	v_pk_fma_f32 v[46:47], v[30:31], v[38:39], v[46:47] neg_lo:[0,0,1] neg_hi:[0,0,1]
	v_pk_mul_f32 v[30:31], v[30:31], v[42:43]
	v_mul_f32_e32 v42, v32, v44
	v_pk_fma_f32 v[26:27], v[26:27], v[38:39], v[30:31]
	v_mul_f32_e32 v30, v32, v40
	v_mul_f32_e32 v38, v28, v44
	v_mul_f32_e32 v40, v28, v40
	v_mov_b32_e32 v28, v33
	v_mov_b32_e32 v44, v41
	v_pk_mul_f32 v[48:49], v[28:29], v[44:45]
	v_mov_b32_e32 v32, v29
	v_cndmask_b32_e32 v0, 1.0, v203, vcc
	v_mov_b32_e32 v31, v48
	v_mov_b32_e32 v39, v49
	v_pk_mul_f32 v[28:29], v[32:33], v[44:45]
	v_pk_mul_f32 v[46:47], v[0:1], v[46:47] op_sel_hi:[0,1]
	v_pk_add_f32 v[30:31], v[30:31], v[38:39] neg_lo:[0,1] neg_hi:[0,1]
	v_mov_b32_e32 v41, v28
	v_mov_b32_e32 v43, v29
	v_pk_mul_f32 v[48:49], v[0:1], v[30:31] op_sel_hi:[0,1]
	v_pk_add_f32 v[28:29], v[40:41], v[42:43]
	v_mov_b64_e32 v[30:31], v[46:47]
	v_pk_mul_f32 v[26:27], v[0:1], v[26:27] op_sel_hi:[0,1]
	v_pk_mul_f32 v[28:29], v[0:1], v[28:29] op_sel_hi:[0,1]
	v_mov_b64_e32 v[32:33], v[48:49]
; DI unsigned pk2(float lo, float hi) { f32x2_t v = {lo, hi}; bf16x2_t b = __builtin_convertvector(v, bf16x2_t); return __builtin_bit_cast(unsigned, b); }
;     DI void operator()(const f32x4 (&acc)[2][2][4][2], const Unit& u, int wr, int wc, int fr, int fq) const {
;     ...
;         epi_iter(acc, u, wr, wc, fr, fq, [&](int row, int col, f32x4 v0, f32x4 v1) {
;             if (col >= lo && col < hi) {
;                 const int i0 = ((col - lo) & 63) >> 1;
;                 const f32x4 c4 = *(const f32x4*)(cp + (size_t)row * 32 + i0), s4 = *(const f32x4*)(sp + (size_t)row * 32 + i0);
;                 const float sc = (col - lo) < 512 ? 0.125f * LOG2E : 1.f;
;                 for (int e = 0; e < 4; ++e) { const float y1 = (v0[e] * c4[e] - v1[e] * s4[e]) * sc, y2 = (v1[e] * c4[e] + v0[e] * s4[e]) * sc; v0[e] = y1; v1[e] = y2; }
;             }
;             u32x4 w; w.x = pk2(v0[0], v0[1]); w.y = pk2(v0[2], v0[3]); w.z = pk2(v1[0], v1[1]); w.w = pk2(v1[2], v1[3]);
;             *(u32x4*)(Op + (size_t)row * ld + col) = w;
.LBB0_263:
	s_or_b64 exec, exec, s[2:3]
	v_cvt_pk_bf16_f32 v30, v30, v31
	v_cvt_pk_bf16_f32 v31, v32, v33
	v_cvt_pk_bf16_f32 v32, v26, v27
	v_mad_i64_i32 v[26:27], s[2:3], v36, s10, 0
	v_lshl_add_u64 v[26:27], v[26:27], 1, s[4:5]
	v_cvt_pk_bf16_f32 v33, v28, v29
	v_lshl_add_u64 v[26:27], v[142:143], 1, v[26:27]
	global_store_dwordx4 v[26:27], v[30:33], off
	s_and_saveexec_b64 s[2:3], s[0:1]
	s_cbranch_execz .LBB0_265
	v_lshlrev_b64 v[32:33], 2, v[34:35]
	v_lshlrev_b32_e32 v0, 1, v142
	v_lshl_add_u64 v[28:29], s[66:67], 0, v[32:33]
	v_and_b32_e32 v0, 0x70, v0
	v_lshl_add_u64 v[32:33], s[6:7], 0, v[32:33]
	v_lshl_add_u64 v[28:29], v[28:29], 0, v[0:1]
	v_lshl_add_u64 v[32:33], v[32:33], 0, v[0:1]
	v_cmp_gt_i32_e32 vcc, s82, v142
	v_mov_b32_e32 v28, v236
	v_mov_b32_e32 v29, v237
	v_mov_b32_e32 v30, v238
	v_mov_b32_e32 v31, v239
	v_mov_b32_e32 v32, v240
	v_mov_b32_e32 v33, v241
	v_mov_b32_e32 v34, v242
	v_mov_b32_e32 v35, v243
	v_pk_mul_f32 v[36:37], v[18:19], v[32:33]
	s_nop 0
	v_pk_fma_f32 v[36:37], v[22:23], v[28:29], v[36:37] neg_lo:[0,0,1] neg_hi:[0,0,1]
	v_pk_mul_f32 v[22:23], v[22:23], v[32:33]
	v_mul_f32_e32 v32, v24, v34
	v_pk_fma_f32 v[18:19], v[18:19], v[28:29], v[22:23]
	v_mul_f32_e32 v22, v24, v30
	v_mul_f32_e32 v28, v20, v34
	v_mul_f32_e32 v30, v20, v30
	v_mov_b32_e32 v20, v25
	v_mov_b32_e32 v34, v31
	v_pk_mul_f32 v[38:39], v[20:21], v[34:35]
	v_mov_b32_e32 v24, v21
	v_cndmask_b32_e32 v0, 1.0, v203, vcc
	v_mov_b32_e32 v23, v38
	v_mov_b32_e32 v29, v39
	v_pk_mul_f32 v[20:21], v[24:25], v[34:35]
	v_pk_mul_f32 v[36:37], v[0:1], v[36:37] op_sel_hi:[0,1]
	v_pk_add_f32 v[22:23], v[22:23], v[28:29] neg_lo:[0,1] neg_hi:[0,1]
	v_mov_b32_e32 v31, v20
	v_mov_b32_e32 v33, v21
	v_pk_mul_f32 v[38:39], v[0:1], v[22:23] op_sel_hi:[0,1]
	v_pk_add_f32 v[20:21], v[30:31], v[32:33]
	v_mov_b64_e32 v[22:23], v[36:37]
	v_pk_mul_f32 v[18:19], v[0:1], v[18:19] op_sel_hi:[0,1]
	v_pk_mul_f32 v[20:21], v[0:1], v[20:21] op_sel_hi:[0,1]
	v_mov_b64_e32 v[24:25], v[38:39]
.LBB0_265:
	s_or_b64 exec, exec, s[2:3]
	v_cvt_pk_bf16_f32 v22, v22, v23
	v_cvt_pk_bf16_f32 v23, v24, v25
	v_cvt_pk_bf16_f32 v25, v20, v21
	v_add_u32_e32 v20, 0xb0, v144
	v_ashrrev_i32_e32 v21, 31, v20
	v_cvt_pk_bf16_f32 v24, v18, v19
	v_lshlrev_b64 v[18:19], 5, v[20:21]
	global_store_dwordx4 v[26:27], v[22:25], off offset:256
	s_and_saveexec_b64 s[2:3], s[56:57]
	s_cbranch_execz .LBB0_267
	v_lshlrev_b64 v[26:27], 2, v[18:19]
	v_lshlrev_b32_e32 v0, 1, v142
	v_lshl_add_u64 v[22:23], s[66:67], 0, v[26:27]
	v_and_b32_e32 v0, 0x70, v0
	v_lshl_add_u64 v[26:27], s[6:7], 0, v[26:27]
	v_lshl_add_u64 v[22:23], v[22:23], 0, v[0:1]
	v_lshl_add_u64 v[26:27], v[26:27], 0, v[0:1]
	v_cmp_gt_i32_e32 vcc, s69, v142
	s_waitcnt vmcnt(12)
	v_mov_b32_e32 v22, v170
	v_mov_b32_e32 v23, v171
	v_mov_b32_e32 v24, v172
	v_mov_b32_e32 v25, v173
	v_mov_b32_e32 v26, v174
	v_mov_b32_e32 v27, v175
	v_mov_b32_e32 v28, v176
	v_mov_b32_e32 v29, v177
	v_pk_mul_f32 v[30:31], v[10:11], v[26:27]
	s_nop 0
	v_pk_fma_f32 v[30:31], v[14:15], v[22:23], v[30:31] neg_lo:[0,0,1] neg_hi:[0,0,1]
	v_pk_mul_f32 v[14:15], v[14:15], v[26:27]
	v_mul_f32_e32 v26, v16, v28
	v_pk_fma_f32 v[10:11], v[10:11], v[22:23], v[14:15]
	v_mul_f32_e32 v14, v16, v24
	v_mul_f32_e32 v22, v12, v28
	v_mul_f32_e32 v24, v12, v24
	v_mov_b32_e32 v12, v17
	v_mov_b32_e32 v28, v25
	v_pk_mul_f32 v[32:33], v[12:13], v[28:29]
	v_mov_b32_e32 v16, v13
	v_cndmask_b32_e32 v0, 1.0, v203, vcc
	v_mov_b32_e32 v15, v32
	v_mov_b32_e32 v23, v33
	v_pk_mul_f32 v[12:13], v[16:17], v[28:29]
	v_pk_mul_f32 v[30:31], v[0:1], v[30:31] op_sel_hi:[0,1]
	v_pk_add_f32 v[14:15], v[14:15], v[22:23] neg_lo:[0,1] neg_hi:[0,1]
	v_mov_b32_e32 v25, v12
	v_mov_b32_e32 v27, v13
	v_pk_mul_f32 v[32:33], v[0:1], v[14:15] op_sel_hi:[0,1]
	v_pk_add_f32 v[12:13], v[24:25], v[26:27]
	v_mov_b64_e32 v[14:15], v[30:31]
	v_pk_mul_f32 v[10:11], v[0:1], v[10:11] op_sel_hi:[0,1]
	v_pk_mul_f32 v[12:13], v[0:1], v[12:13] op_sel_hi:[0,1]
	v_mov_b64_e32 v[16:17], v[32:33]
.LBB0_267:
	s_or_b64 exec, exec, s[2:3]
	v_cvt_pk_bf16_f32 v14, v14, v15
	v_cvt_pk_bf16_f32 v15, v16, v17
	v_cvt_pk_bf16_f32 v16, v10, v11
	v_mad_i64_i32 v[10:11], s[2:3], v20, s10, 0
	v_lshl_add_u64 v[10:11], v[10:11], 1, s[4:5]
	v_cvt_pk_bf16_f32 v17, v12, v13
	v_lshl_add_u64 v[10:11], v[142:143], 1, v[10:11]
	global_store_dwordx4 v[10:11], v[14:17], off
	s_and_saveexec_b64 s[2:3], s[0:1]
	s_cbranch_execz .LBB0_269
	v_lshlrev_b64 v[16:17], 2, v[18:19]
	v_lshlrev_b32_e32 v0, 1, v142
	v_lshl_add_u64 v[12:13], s[66:67], 0, v[16:17]
	v_and_b32_e32 v0, 0x70, v0
	v_lshl_add_u64 v[16:17], s[6:7], 0, v[16:17]
	v_lshl_add_u64 v[12:13], v[12:13], 0, v[0:1]
	v_lshl_add_u64 v[16:17], v[16:17], 0, v[0:1]
	v_cmp_gt_i32_e32 vcc, s82, v142
	v_mov_b32_e32 v12, v170
	v_mov_b32_e32 v13, v171
	v_mov_b32_e32 v14, v172
	v_mov_b32_e32 v15, v173
	v_mov_b32_e32 v16, v174
	v_mov_b32_e32 v17, v175
	v_mov_b32_e32 v18, v176
	v_mov_b32_e32 v19, v177
	v_pk_mul_f32 v[20:21], v[2:3], v[16:17]
	s_nop 0
	v_pk_fma_f32 v[20:21], v[6:7], v[12:13], v[20:21] neg_lo:[0,0,1] neg_hi:[0,0,1]
	v_pk_mul_f32 v[6:7], v[6:7], v[16:17]
	v_mul_f32_e32 v16, v8, v18
	v_pk_fma_f32 v[2:3], v[2:3], v[12:13], v[6:7]
	v_mul_f32_e32 v6, v8, v14
	v_mul_f32_e32 v12, v4, v18
	v_mul_f32_e32 v14, v4, v14
	v_mov_b32_e32 v4, v9
	v_mov_b32_e32 v18, v15
	v_pk_mul_f32 v[22:23], v[4:5], v[18:19]
	v_mov_b32_e32 v8, v5
	v_cndmask_b32_e32 v0, 1.0, v203, vcc
	v_mov_b32_e32 v7, v22
	v_mov_b32_e32 v13, v23
	v_pk_mul_f32 v[4:5], v[8:9], v[18:19]
	v_pk_mul_f32 v[20:21], v[0:1], v[20:21] op_sel_hi:[0,1]
	v_pk_add_f32 v[6:7], v[6:7], v[12:13] neg_lo:[0,1] neg_hi:[0,1]
	v_mov_b32_e32 v15, v4
	v_mov_b32_e32 v17, v5
	v_pk_mul_f32 v[22:23], v[0:1], v[6:7] op_sel_hi:[0,1]
	v_pk_add_f32 v[4:5], v[14:15], v[16:17]
	v_mov_b64_e32 v[6:7], v[20:21]
	v_pk_mul_f32 v[2:3], v[0:1], v[2:3] op_sel_hi:[0,1]
	v_pk_mul_f32 v[4:5], v[0:1], v[4:5] op_sel_hi:[0,1]
	v_mov_b64_e32 v[8:9], v[22:23]
